# L2 prefetch helpers: idle WGs in scan phase touch next records of the same-XCD chain, paced by a progress word
# speedup vs baseline: 1.0359x; 1.0359x over previous
.LBB0_21:
	s_lshr_b32 s95, s85, 6
	s_cmp_gt_u32 s2, 63
	s_cbranch_scc1 .Lpf_noinit
	s_cmp_lg_u32 s85, 0
	s_cbranch_scc1 .Lpf_noinit
	s_add_u32 s98, s54, 0x1ec04000
	s_addc_u32 s99, s55, 0
	s_lshl_b32 s100, s2, 8
	s_add_u32 s98, s98, s100
	s_addc_u32 s99, s99, 0
	v_mov_b32_e32 v239, 0
	global_store_dword v239, v239, s[98:99] sc0 sc1
.Lpf_noinit:
	s_add_u32 s6, s54, 0x1a00000
	s_addc_u32 s7, s55, 0
	s_cmp_lt_i32 s56, 1
	s_cselect_b64 s[8:9], -1, 0
	s_cmp_gt_i32 s57, 0
	s_cselect_b64 s[0:1], -1, 0
	s_and_b64 s[0:1], s[8:9], s[0:1]
	s_andn2_b64 vcc, exec, s[0:1]
	s_cbranch_vccnz .LBB0_55
	v_mbcnt_lo_u32_b32 v0, -1, 0
	s_and_b32 s4, s85, 0xffffffc0
	v_mbcnt_hi_u32_b32 v128, -1, v0
	v_add_u32_e32 v146, s4, v128
	v_lshl_add_u32 v0, s2, 9, v146
	s_mov_b32 s0, 0x8000
	v_cmp_gt_i32_e32 vcc, s0, v0
	s_and_saveexec_b64 s[12:13], vcc
	s_cbranch_execz .LBB0_30
	s_lshl_b32 s34, s58, 9
	v_cvt_f32_u32_e32 v2, s34
	v_add_u32_e32 v1, s34, v0
	v_mov_b32_e32 v3, s34
	v_cmp_gt_i32_e32 vcc, s0, v1
	v_rcp_iflag_f32_e32 v2, v2
	s_sub_i32 s3, 0, s34
	v_max_i32_e32 v4, 0x8000, v1
	v_addc_co_u32_e64 v3, s[0:1], v0, v3, vcc
	v_mul_f32_e32 v2, 0x4f7ffffe, v2
	v_cvt_u32_f32_e32 v2, v2
	v_sub_u32_e32 v3, v4, v3
	s_mov_b64 s[60:61], -1
	v_mul_lo_u32 v4, s3, v2
	v_mul_hi_u32 v4, v2, v4
	v_add_u32_e32 v2, v2, v4
	v_mul_hi_u32 v2, v3, v2
	v_mul_lo_u32 v4, v2, s34
	v_sub_u32_e32 v3, v3, v4
	v_add_u32_e32 v5, 1, v2
	v_cmp_le_u32_e64 s[0:1], s34, v3
	v_subrev_u32_e32 v4, s34, v3
	s_nop 0
	v_cndmask_b32_e64 v2, v2, v5, s[0:1]
	v_cndmask_b32_e64 v3, v3, v4, s[0:1]
	v_add_u32_e32 v4, 1, v2
	v_cmp_le_u32_e64 s[0:1], s34, v3
	s_nop 1
	v_cndmask_b32_e64 v2, v2, v4, s[0:1]
	v_addc_co_u32_e32 v4, vcc, 1, v2, vcc
	v_cmp_lt_u32_e32 vcc, 1, v4
	s_and_saveexec_b64 s[0:1], vcc
	s_cbranch_execz .LBB0_27
	s_add_u32 s60, s54, 0x1ac0000
	s_addc_u32 s61, s55, 0
	v_and_b32_e32 v5, -2, v4
	s_lshl_b32 s3, s58, 10
	s_mov_b32 s5, s3
	s_mov_b64 s[62:63], 0
	v_mov_b32_e32 v6, 0
	v_mov_b32_e32 v7, v5
	v_mov_b64_e32 v[2:3], v[0:1]

.LBB0_494:
	v_lshl_add_u64 v[12:13], v[2:3], 0, s[0:1]
	v_add_co_u32_e32 v144, vcc, s6, v12
	global_load_dword v142, v[12:13], off
	s_nop 0
	v_addc_co_u32_e32 v145, vcc, 0, v13, vcc
	v_add_co_u32_e32 v146, vcc, s7, v12
	v_mov_b32_e32 v138, s3
	s_nop 0
	v_addc_co_u32_e32 v147, vcc, 0, v13, vcc
	v_add_co_u32_e32 v148, vcc, s8, v12
	ds_read_b128 v[14:17], v138
	ds_read_b128 v[18:21], v138 offset:16
	ds_read_b128 v[22:25], v138 offset:32
	ds_read_b128 v[26:29], v138 offset:48
	v_addc_co_u32_e32 v149, vcc, 0, v13, vcc
	v_add_co_u32_e32 v150, vcc, s9, v12
	ds_read_b128 v[30:33], v138 offset:4096
	ds_read_b128 v[34:37], v138 offset:4112
	ds_read_b128 v[38:41], v138 offset:8192
	ds_read_b128 v[42:45], v138 offset:8208
	ds_read_b128 v[46:49], v138 offset:12288
	ds_read_b128 v[50:53], v138 offset:12304
	ds_read_b128 v[54:57], v138 offset:16384
	ds_read_b128 v[58:61], v138 offset:16400
	ds_read_b128 v[62:65], v138 offset:20480
	ds_read_b128 v[66:69], v138 offset:20496
	ds_read_b128 v[70:73], v138 offset:24576
	ds_read_b128 v[74:77], v138 offset:24592
	ds_read_b128 v[78:81], v138 offset:28672
	ds_read_b128 v[82:85], v138 offset:28688
	v_addc_co_u32_e32 v151, vcc, 0, v13, vcc
	v_add_co_u32_e32 v152, vcc, s12, v12
	ds_read_b128 v[86:89], v138 offset:4128
	ds_read_b128 v[90:93], v138 offset:4144
	ds_read_b128 v[94:97], v138 offset:8224
	ds_read_b128 v[98:101], v138 offset:8240
	ds_read_b128 v[102:105], v138 offset:12320
	ds_read_b128 v[106:109], v138 offset:12336
	ds_read_b128 v[110:113], v138 offset:16416
	ds_read_b128 v[114:117], v138 offset:16432
	ds_read_b128 v[118:121], v138 offset:20512
	ds_read_b128 v[122:125], v138 offset:20528
	ds_read_b128 v[126:129], v138 offset:24608
	ds_read_b128 v[130:133], v138 offset:24624
	ds_read_b128 v[134:137], v138 offset:28704
	ds_read_b128 v[138:141], v138 offset:28720
	v_addc_co_u32_e32 v153, vcc, 0, v13, vcc
	v_add_co_u32_e32 v154, vcc, s13, v12
	s_waitcnt lgkmcnt(14)
	v_mov_b32_e32 v172, v14
	v_addc_co_u32_e32 v155, vcc, 0, v13, vcc
	v_add_co_u32_e32 v156, vcc, s14, v12
	v_mov_b32_e32 v173, v30
	s_nop 0
	v_addc_co_u32_e32 v157, vcc, 0, v13, vcc
	v_add_co_u32_e32 v158, vcc, s15, v12
	v_mov_b32_e32 v174, v38
	s_nop 0
	v_addc_co_u32_e32 v159, vcc, 0, v13, vcc
	v_add_co_u32_e32 v160, vcc, s16, v12
	v_mov_b32_e32 v175, v46
	s_nop 0
	v_addc_co_u32_e32 v161, vcc, 0, v13, vcc
	v_add_co_u32_e32 v162, vcc, s17, v12
	v_mov_b32_e32 v176, v54
	s_nop 0
	v_addc_co_u32_e32 v163, vcc, 0, v13, vcc
	v_add_co_u32_e32 v164, vcc, s26, v12
	v_mov_b32_e32 v177, v62
	s_nop 0
	v_addc_co_u32_e32 v165, vcc, 0, v13, vcc
	v_add_co_u32_e32 v166, vcc, s27, v12
	v_mov_b32_e32 v178, v70
	s_nop 0
	v_addc_co_u32_e32 v167, vcc, 0, v13, vcc
	v_add_co_u32_e32 v168, vcc, s28, v12
	v_mov_b32_e32 v179, v78
	s_nop 0
	v_addc_co_u32_e32 v169, vcc, 0, v13, vcc
	v_add_co_u32_e32 v170, vcc, s29, v12
	v_mov_b32_e32 v30, v15
	s_nop 0
	v_addc_co_u32_e32 v171, vcc, 0, v13, vcc
	v_add_co_u32_e32 v12, vcc, s34, v12
	v_mov_b32_e32 v46, v39
	s_nop 0
	v_addc_co_u32_e32 v13, vcc, 0, v13, vcc
	global_load_dword v144, v[144:145], off
	s_nop 0
	global_load_dword v146, v[146:147], off
	s_nop 0
	global_load_dword v148, v[148:149], off
	s_nop 0
	global_load_dword v150, v[150:151], off
	s_nop 0
	global_load_dword v152, v[152:153], off
	s_nop 0
	global_load_dword v154, v[154:155], off
	s_nop 0
	global_load_dword v156, v[156:157], off
	s_nop 0
	global_load_dword v158, v[158:159], off
	s_nop 0
	global_load_dword v160, v[160:161], off
	s_nop 0
	global_load_dword v162, v[162:163], off
	s_nop 0
	global_load_dword v164, v[164:165], off
	s_nop 0
	global_load_dword v166, v[166:167], off
	s_nop 0
	global_load_dword v168, v[168:169], off
	s_nop 0
	global_load_dword v170, v[170:171], off
	s_nop 0
	global_load_dword v12, v[12:13], off
	v_mov_b32_e32 v62, v55
	v_mov_b32_e32 v78, v71
	v_mov_b32_e32 v14, v16
	v_mov_b32_e32 v15, v32
	v_mov_b32_e32 v38, v40
	v_mov_b32_e32 v39, v48
	s_waitcnt vmcnt(15)
	v_pk_fma_f32 v[10:11], v[142:143], v[172:173], v[10:11] op_sel_hi:[0,1,1]
	v_pk_fma_f32 v[8:9], v[142:143], v[174:175], v[8:9] op_sel_hi:[0,1,1]
	v_pk_fma_f32 v[6:7], v[142:143], v[176:177], v[6:7] op_sel_hi:[0,1,1]
	v_pk_fma_f32 v[4:5], v[142:143], v[178:179], v[4:5] op_sel_hi:[0,1,1]
	v_mov_b32_e32 v54, v56
	v_mov_b32_e32 v55, v64
	v_mov_b32_e32 v70, v72
	v_mov_b32_e32 v71, v80
	v_mov_b32_e32 v32, v17
	v_mov_b32_e32 v48, v41
	v_mov_b32_e32 v64, v57
	v_mov_b32_e32 v80, v73
	v_mov_b32_e32 v16, v18
	v_mov_b32_e32 v17, v34
	v_mov_b32_e32 v40, v42
	v_mov_b32_e32 v41, v50
	v_mov_b32_e32 v56, v58
	v_mov_b32_e32 v57, v66
	v_mov_b32_e32 v72, v74
	v_mov_b32_e32 v73, v82
	v_mov_b32_e32 v34, v19
	v_mov_b32_e32 v50, v43
	v_mov_b32_e32 v66, v59
	v_mov_b32_e32 v82, v75
	v_mov_b32_e32 v18, v20
	v_mov_b32_e32 v19, v36
	v_mov_b32_e32 v42, v44
	v_mov_b32_e32 v43, v52
	v_mov_b32_e32 v58, v60
	v_mov_b32_e32 v59, v68
	v_mov_b32_e32 v74, v76
	v_mov_b32_e32 v75, v84
	v_mov_b32_e32 v36, v21
	v_mov_b32_e32 v52, v45
	v_mov_b32_e32 v68, v61
	v_mov_b32_e32 v84, v77
	v_mov_b32_e32 v20, v22
	s_waitcnt lgkmcnt(13)
	v_mov_b32_e32 v21, v86
	s_waitcnt lgkmcnt(11)
	v_mov_b32_e32 v44, v94
	s_waitcnt lgkmcnt(9)
	v_mov_b32_e32 v45, v102
	s_waitcnt lgkmcnt(7)
	v_mov_b32_e32 v60, v110
	s_waitcnt lgkmcnt(5)
	v_mov_b32_e32 v61, v118
	s_waitcnt lgkmcnt(3)
	v_mov_b32_e32 v76, v126
	s_waitcnt lgkmcnt(1)
	v_mov_b32_e32 v77, v134
	v_mov_b32_e32 v86, v23
	v_mov_b32_e32 v102, v95
	v_mov_b32_e32 v118, v111
	v_mov_b32_e32 v134, v127
	v_mov_b32_e32 v22, v24
	v_mov_b32_e32 v23, v88
	v_mov_b32_e32 v94, v96
	v_mov_b32_e32 v95, v104
	v_mov_b32_e32 v110, v112
	v_mov_b32_e32 v111, v120
	v_mov_b32_e32 v126, v128
	v_mov_b32_e32 v127, v136
	v_mov_b32_e32 v88, v25
	v_mov_b32_e32 v104, v97
	v_mov_b32_e32 v120, v113
	s_waitcnt vmcnt(14)
	v_pk_fma_f32 v[10:11], v[144:145], v[30:31], v[10:11] op_sel_hi:[0,1,1]
	v_pk_fma_f32 v[8:9], v[144:145], v[46:47], v[8:9] op_sel_hi:[0,1,1]
	v_pk_fma_f32 v[6:7], v[144:145], v[62:63], v[6:7] op_sel_hi:[0,1,1]
	v_pk_fma_f32 v[4:5], v[144:145], v[78:79], v[4:5] op_sel_hi:[0,1,1]
	s_waitcnt vmcnt(13)
	v_pk_fma_f32 v[10:11], v[146:147], v[14:15], v[10:11] op_sel_hi:[0,1,1]
	v_pk_fma_f32 v[8:9], v[146:147], v[38:39], v[8:9] op_sel_hi:[0,1,1]
	v_pk_fma_f32 v[6:7], v[146:147], v[54:55], v[6:7] op_sel_hi:[0,1,1]
	v_pk_fma_f32 v[4:5], v[146:147], v[70:71], v[4:5] op_sel_hi:[0,1,1]
	s_waitcnt vmcnt(12)
	v_pk_fma_f32 v[10:11], v[148:149], v[32:33], v[10:11] op_sel_hi:[0,1,1]
	v_pk_fma_f32 v[8:9], v[148:149], v[48:49], v[8:9] op_sel_hi:[0,1,1]
	v_pk_fma_f32 v[6:7], v[148:149], v[64:65], v[6:7] op_sel_hi:[0,1,1]
	v_pk_fma_f32 v[4:5], v[148:149], v[80:81], v[4:5] op_sel_hi:[0,1,1]
	s_waitcnt vmcnt(11)
	v_pk_fma_f32 v[10:11], v[150:151], v[16:17], v[10:11] op_sel_hi:[0,1,1]
	v_pk_fma_f32 v[8:9], v[150:151], v[40:41], v[8:9] op_sel_hi:[0,1,1]
	v_pk_fma_f32 v[6:7], v[150:151], v[56:57], v[6:7] op_sel_hi:[0,1,1]
	v_pk_fma_f32 v[4:5], v[150:151], v[72:73], v[4:5] op_sel_hi:[0,1,1]
	s_waitcnt vmcnt(10)
	v_pk_fma_f32 v[10:11], v[152:153], v[34:35], v[10:11] op_sel_hi:[0,1,1]
	v_pk_fma_f32 v[8:9], v[152:153], v[50:51], v[8:9] op_sel_hi:[0,1,1]
	v_pk_fma_f32 v[6:7], v[152:153], v[66:67], v[6:7] op_sel_hi:[0,1,1]
	v_pk_fma_f32 v[4:5], v[152:153], v[82:83], v[4:5] op_sel_hi:[0,1,1]
	s_waitcnt vmcnt(9)
	v_pk_fma_f32 v[10:11], v[154:155], v[18:19], v[10:11] op_sel_hi:[0,1,1]
	v_pk_fma_f32 v[8:9], v[154:155], v[42:43], v[8:9] op_sel_hi:[0,1,1]
	v_pk_fma_f32 v[6:7], v[154:155], v[58:59], v[6:7] op_sel_hi:[0,1,1]
	v_pk_fma_f32 v[4:5], v[154:155], v[74:75], v[4:5] op_sel_hi:[0,1,1]
	s_waitcnt vmcnt(8)
	v_pk_fma_f32 v[10:11], v[156:157], v[36:37], v[10:11] op_sel_hi:[0,1,1]
	v_pk_fma_f32 v[8:9], v[156:157], v[52:53], v[8:9] op_sel_hi:[0,1,1]
	v_pk_fma_f32 v[6:7], v[156:157], v[68:69], v[6:7] op_sel_hi:[0,1,1]
	v_pk_fma_f32 v[4:5], v[156:157], v[84:85], v[4:5] op_sel_hi:[0,1,1]
	s_waitcnt vmcnt(7)
	v_pk_fma_f32 v[10:11], v[158:159], v[20:21], v[10:11] op_sel_hi:[0,1,1]
	v_pk_fma_f32 v[8:9], v[158:159], v[44:45], v[8:9] op_sel_hi:[0,1,1]
	v_pk_fma_f32 v[6:7], v[158:159], v[60:61], v[6:7] op_sel_hi:[0,1,1]
	v_pk_fma_f32 v[4:5], v[158:159], v[76:77], v[4:5] op_sel_hi:[0,1,1]
	s_waitcnt vmcnt(6)
	v_pk_fma_f32 v[10:11], v[160:161], v[86:87], v[10:11] op_sel_hi:[0,1,1]
	v_pk_fma_f32 v[8:9], v[160:161], v[102:103], v[8:9] op_sel_hi:[0,1,1]
	v_pk_fma_f32 v[6:7], v[160:161], v[118:119], v[6:7] op_sel_hi:[0,1,1]
	v_pk_fma_f32 v[4:5], v[160:161], v[134:135], v[4:5] op_sel_hi:[0,1,1]
	v_mov_b32_e32 v136, v129
	s_waitcnt vmcnt(5)
	v_pk_fma_f32 v[10:11], v[162:163], v[22:23], v[10:11] op_sel_hi:[0,1,1]
	v_pk_fma_f32 v[8:9], v[162:163], v[94:95], v[8:9] op_sel_hi:[0,1,1]
	v_pk_fma_f32 v[6:7], v[162:163], v[110:111], v[6:7] op_sel_hi:[0,1,1]
	v_pk_fma_f32 v[4:5], v[162:163], v[126:127], v[4:5] op_sel_hi:[0,1,1]
	v_mov_b32_e32 v24, v26
	v_mov_b32_e32 v25, v90
	v_mov_b32_e32 v96, v98
	v_mov_b32_e32 v97, v106
	v_mov_b32_e32 v112, v114
	v_mov_b32_e32 v113, v122
	v_mov_b32_e32 v128, v130
	s_waitcnt lgkmcnt(0)
	v_mov_b32_e32 v129, v138
	s_waitcnt vmcnt(4)
	v_pk_fma_f32 v[10:11], v[164:165], v[88:89], v[10:11] op_sel_hi:[0,1,1]
	v_pk_fma_f32 v[8:9], v[164:165], v[104:105], v[8:9] op_sel_hi:[0,1,1]
	v_pk_fma_f32 v[6:7], v[164:165], v[120:121], v[6:7] op_sel_hi:[0,1,1]
	v_pk_fma_f32 v[4:5], v[164:165], v[136:137], v[4:5] op_sel_hi:[0,1,1]
	v_mov_b32_e32 v90, v27
	v_mov_b32_e32 v106, v99
	v_mov_b32_e32 v122, v115
	v_mov_b32_e32 v138, v131
	s_waitcnt vmcnt(3)
	v_pk_fma_f32 v[10:11], v[166:167], v[24:25], v[10:11] op_sel_hi:[0,1,1]
	v_pk_fma_f32 v[8:9], v[166:167], v[96:97], v[8:9] op_sel_hi:[0,1,1]
	v_pk_fma_f32 v[6:7], v[166:167], v[112:113], v[6:7] op_sel_hi:[0,1,1]
	v_pk_fma_f32 v[4:5], v[166:167], v[128:129], v[4:5] op_sel_hi:[0,1,1]
	s_add_u32 s0, s0, 0x40000
	v_mov_b32_e32 v26, v28
	v_mov_b32_e32 v27, v92
	v_mov_b32_e32 v98, v100
	v_mov_b32_e32 v99, v108
	v_mov_b32_e32 v114, v116
	v_mov_b32_e32 v115, v124
	v_mov_b32_e32 v130, v132
	v_mov_b32_e32 v131, v140
	s_waitcnt vmcnt(2)
	v_pk_fma_f32 v[10:11], v[168:169], v[90:91], v[10:11] op_sel_hi:[0,1,1]
	v_pk_fma_f32 v[8:9], v[168:169], v[106:107], v[8:9] op_sel_hi:[0,1,1]
	v_pk_fma_f32 v[6:7], v[168:169], v[122:123], v[6:7] op_sel_hi:[0,1,1]
	v_pk_fma_f32 v[4:5], v[168:169], v[138:139], v[4:5] op_sel_hi:[0,1,1]
	s_addc_u32 s1, s1, 0
	s_add_i32 s3, s3, 64
	v_mov_b32_e32 v92, v29
	v_mov_b32_e32 v108, v101
	v_mov_b32_e32 v124, v117
	v_mov_b32_e32 v140, v133
	s_waitcnt vmcnt(1)
	v_pk_fma_f32 v[10:11], v[170:171], v[26:27], v[10:11] op_sel_hi:[0,1,1]
	v_pk_fma_f32 v[8:9], v[170:171], v[98:99], v[8:9] op_sel_hi:[0,1,1]
	v_pk_fma_f32 v[6:7], v[170:171], v[114:115], v[6:7] op_sel_hi:[0,1,1]
	v_pk_fma_f32 v[4:5], v[170:171], v[130:131], v[4:5] op_sel_hi:[0,1,1]
	s_cmp_lg_u32 s0, 0x1000000
	s_waitcnt vmcnt(0)
	v_pk_fma_f32 v[10:11], v[12:13], v[92:93], v[10:11] op_sel_hi:[0,1,1]
	v_pk_fma_f32 v[8:9], v[12:13], v[108:109], v[8:9] op_sel_hi:[0,1,1]
	v_pk_fma_f32 v[6:7], v[12:13], v[124:125], v[6:7] op_sel_hi:[0,1,1]
	v_pk_fma_f32 v[4:5], v[12:13], v[140:141], v[4:5] op_sel_hi:[0,1,1]
	s_cbranch_scc1 .LBB0_494
	v_lshl_add_u64 v[0:1], v[0:1], 2, s[54:55]
	v_add_co_u32_e32 v2, vcc, 0x1a80000, v0
	s_nop 1
	v_addc_co_u32_e32 v3, vcc, 0, v1, vcc
	global_store_dword v[2:3], v10, off
	v_add_co_u32_e32 v2, vcc, 0x1a84000, v0
	s_nop 1
	v_addc_co_u32_e32 v3, vcc, 0, v1, vcc
	global_store_dword v[2:3], v11, off
	v_add_co_u32_e32 v2, vcc, 0x1a88000, v0
	s_nop 1
	v_addc_co_u32_e32 v3, vcc, 0, v1, vcc
	global_store_dword v[2:3], v8, off
	v_add_co_u32_e32 v2, vcc, 0x1a8c000, v0
	s_nop 1
	v_addc_co_u32_e32 v3, vcc, 0, v1, vcc
	global_store_dword v[2:3], v9, off
	v_add_co_u32_e32 v2, vcc, 0x1a90000, v0
	s_nop 1
	v_addc_co_u32_e32 v3, vcc, 0, v1, vcc
	global_store_dword v[2:3], v6, off
	v_add_co_u32_e32 v2, vcc, 0x1a94000, v0
	s_nop 1
	v_addc_co_u32_e32 v3, vcc, 0, v1, vcc
	global_store_dword v[2:3], v7, off
	v_add_co_u32_e32 v2, vcc, 0x1a98000, v0
	s_nop 1
	v_addc_co_u32_e32 v3, vcc, 0, v1, vcc
	v_add_co_u32_e32 v0, vcc, 0x1a9c000, v0
	global_store_dword v[2:3], v4, off
	s_nop 0
	v_addc_co_u32_e32 v1, vcc, 0, v1, vcc
	global_store_dword v[0:1], v5, off
	s_branch .LBB0_496
.Lpf_entry:
	s_cmp_lg_u32 s95, 0
	s_cbranch_scc1 .LBB0_496
	s_add_i32 s0, s2, -72
	s_lshr_b32 s1, s0, 3
	s_and_b32 s3, s2, 7
	s_and_b32 s6, s1, 7
	s_lshl_b32 s7, s6, 3
	s_or_b32 s3, s3, s7
	s_lshr_b32 s1, s1, 3
	s_cmp_eq_u32 s6, 7
	s_cselect_b32 s7, 2, 3
	s_add_u32 s98, s54, 0x1ec04000
	s_addc_u32 s99, s55, 0
	s_lshl_b32 s8, s3, 8
	s_add_u32 s98, s98, s8
	s_addc_u32 s99, s99, 0
	s_lshr_b32 s8, s3, 1
	s_add_u32 s14, s54, 0x15c00000
	s_addc_u32 s15, s55, 0
	s_mov_b32 s9, 0xe000
	s_mov_b32 s12, 0x380000
	s_bitcmp1_b32 s3, 0
	s_cmov_b32 s9, 0x12000
	s_cmov_b32 s12, 0x480000
	s_cselect_b32 s14, s14, s52
	s_cselect_b32 s15, s15, s53
	s_mul_i32 s13, s12, s8
	s_add_u32 s12, s14, s13
	s_addc_u32 s13, s15, 0
	s_lshr_b32 s16, s9, 6
	s_cmp_eq_u32 s7, 2
	s_cbranch_scc1 .Lpf_nh2
	s_add_i32 s17, s16, 2
	s_mul_i32 s17, s17, 0xaaab
	s_lshr_b32 s17, s17, 17
	s_branch .Lpf_per
.Lpf_nh2:
	s_lshr_b32 s17, s16, 1
.Lpf_per:
	s_mul_i32 s26, s1, s17
	s_add_i32 s27, s26, s17
	s_min_u32 s27, s27, s16
	s_add_i32 s27, s27, -1
	v_mbcnt_lo_u32_b32 v1, -1, 0
	v_mbcnt_hi_u32_b32 v1, -1, v1
	v_add_u32_e32 v1, s26, v1
	v_mov_b32_e32 v0, 0
	v_min_u32_e32 v2, s27, v1
	v_lshlrev_b32_e32 v2, 6, v2
	v_add_u32_e32 v21, 64, v1
	v_min_u32_e32 v3, s27, v21
	v_lshlrev_b32_e32 v3, 6, v3
	v_add_u32_e32 v21, 128, v1
	v_min_u32_e32 v4, s27, v21
	v_lshlrev_b32_e32 v4, 6, v4
	v_add_u32_e32 v21, 192, v1
	v_min_u32_e32 v5, s27, v21
	v_lshlrev_b32_e32 v5, 6, v5
	v_add_u32_e32 v21, 256, v1
	v_min_u32_e32 v6, s27, v21
	v_lshlrev_b32_e32 v6, 6, v6
	v_add_u32_e32 v21, 320, v1
	v_min_u32_e32 v7, s27, v21
	v_lshlrev_b32_e32 v7, 6, v7
	v_add_u32_e32 v21, 384, v1
	v_min_u32_e32 v8, s27, v21
	v_lshlrev_b32_e32 v8, 6, v8
	v_add_u32_e32 v21, 448, v1
	v_min_u32_e32 v9, s27, v21
	v_lshlrev_b32_e32 v9, 6, v9
	v_add_u32_e32 v21, 512, v1
	v_min_u32_e32 v10, s27, v21
	v_lshlrev_b32_e32 v10, 6, v10
	s_mov_b32 s6, 0
	s_mov_b32 s16, 0
.Lpf_poll:
	global_load_dword v20, v0, s[98:99] sc1
	s_waitcnt vmcnt(0)
	v_readfirstlane_b32 s17, v20
	s_nop 3
	s_add_i32 s17, s17, 5
	s_min_u32 s17, s17, 63
	s_cmp_gt_u32 s6, s17
	s_cbranch_scc1 .Lpf_wait
.Lpf_step:
	s_mul_i32 s28, s6, s9
	s_add_u32 s28, s28, s12
	s_addc_u32 s29, s13, 0
	global_load_dword v11, v2, s[28:29]
	global_load_dword v12, v3, s[28:29]
	global_load_dword v13, v4, s[28:29]
	global_load_dword v14, v5, s[28:29]
	global_load_dword v15, v6, s[28:29]
	global_load_dword v16, v7, s[28:29]
	global_load_dword v17, v8, s[28:29]
	global_load_dword v18, v9, s[28:29]
	global_load_dword v19, v10, s[28:29]
	s_add_i32 s6, s6, 1
	s_cmp_gt_u32 s6, s17
	s_cbranch_scc0 .Lpf_step
	s_cmp_gt_u32 s6, 63
	s_cbranch_scc1 .Lpf_done
	s_branch .Lpf_poll
.Lpf_wait:
	s_sleep 4
	s_add_i32 s16, s16, 1
	s_cmp_lt_u32 s16, 2048
	s_cbranch_scc1 .Lpf_poll
.Lpf_done:
	s_waitcnt vmcnt(0)
.LBB0_496:
	s_mov_b64 s[0:1], 0

.LBB0_507:
	s_and_b64 vcc, exec, s[8:9]
	s_cbranch_vccz .LBB0_520
	s_add_u32 s98, s54, 0x1ec04000
	s_addc_u32 s99, s55, 0
	s_lshl_b32 s100, s2, 8
	s_add_u32 s98, s98, s100
	s_addc_u32 s99, s99, 0
	s_cmp_eq_u32 s95, 4
	s_cselect_b32 s100, 1, 0
	v_mov_b32_e32 v238, 0
	s_and_b64 s[8:9], s[6:7], exec
	s_movk_i32 s8, 0x4000
	s_cselect_b32 s14, s8, 0x8000
	s_mov_b32 s8, 0xc000
	s_mov_b32 s3, 0xe000
	s_cselect_b32 s15, 0x8000, s8
	s_mov_b32 s8, 0x10000
	s_cselect_b32 s3, s3, 0x12000
	s_cselect_b32 s26, 0xc000, s8
	s_and_b32 s8, s85, 0xffffffc0
	s_addk_i32 s8, 0xff00
	s_waitcnt vmcnt(0)
	v_add_u32_e32 v122, s8, v190
	s_add_u32 s8, s16, 0x4000
	s_addc_u32 s9, s17, 0
	s_add_u32 s12, s16, 0x8000
	s_mov_b32 s27, 0
	s_addc_u32 s13, s17, 0
	s_and_b64 vcc, exec, s[0:1]
	s_mov_b64 s[0:1], -1
	s_cbranch_vccnz .LBB0_514
	v_mov_b32_e32 v56, v122
	s_and_b64 s[0:1], s[6:7], exec
	v_lshlrev_b32_e32 v112, 4, v56
	v_ashrrev_i32_e32 v113, 31, v112
	s_cselect_b32 s6, 0, 0x4000
	s_add_u32 s0, s16, 0xc000
	v_lshl_add_u64 v[0:1], s[8:9], 0, v[112:113]
	s_addc_u32 s1, s17, 0
	global_load_dwordx4 v[0:3], v[0:1], off
	v_lshl_add_u64 v[4:5], s[12:13], 0, v[112:113]
	v_add_u32_e32 v114, 0x1000, v112
	global_load_dwordx4 v[4:7], v[4:5], off
	v_lshl_add_u64 v[8:9], s[0:1], 0, v[112:113]
	v_ashrrev_i32_e32 v115, 31, v114
	global_load_dwordx4 v[8:11], v[8:9], off
	v_lshl_add_u64 v[12:13], s[8:9], 0, v[114:115]
	global_load_dwordx4 v[12:15], v[12:13], off
	v_lshl_add_u64 v[16:17], s[12:13], 0, v[114:115]
	v_add_u32_e32 v116, 0x2000, v112
	global_load_dwordx4 v[16:19], v[16:17], off
	v_lshl_add_u64 v[20:21], s[0:1], 0, v[114:115]
	v_ashrrev_i32_e32 v117, 31, v116
	global_load_dwordx4 v[20:23], v[20:21], off
	v_lshl_add_u64 v[24:25], s[8:9], 0, v[116:117]
	global_load_dwordx4 v[24:27], v[24:25], off
	v_lshl_add_u64 v[28:29], s[12:13], 0, v[116:117]
	v_add_u32_e32 v118, 0x3000, v112
	global_load_dwordx4 v[28:31], v[28:29], off
	v_lshl_add_u64 v[32:33], s[0:1], 0, v[116:117]
	v_ashrrev_i32_e32 v119, 31, v118
	global_load_dwordx4 v[32:35], v[32:33], off
	v_lshl_add_u64 v[36:37], s[8:9], 0, v[118:119]
	v_add_u32_e32 v57, 0x100, v56
	global_load_dwordx4 v[36:39], v[36:37], off
	v_lshl_add_u64 v[40:41], s[12:13], 0, v[118:119]
	v_lshl_add_u64 v[44:45], s[0:1], 0, v[118:119]
	s_add_u32 s0, s16, 0x10000
	v_lshlrev_b32_e32 v120, 4, v57
	global_load_dwordx4 v[40:43], v[40:41], off
	s_addc_u32 s1, s17, 0
	v_ashrrev_i32_e32 v121, 31, v120
	global_load_dwordx4 v[44:47], v[44:45], off
	v_lshl_add_u64 v[48:49], s[0:1], 0, v[112:113]
	v_lshl_add_u64 v[52:53], s[0:1], 0, v[120:121]
	v_and_b32_e32 v141, 0xf0, v112
	v_lshrrev_b32_e32 v60, 4, v56
	s_movk_i32 s0, 0x110
	global_load_dwordx4 v[48:51], v[48:49], off
	v_add_u32_e32 v58, 0, v141
	v_mul_lo_u32 v123, v60, s0
	global_load_dwordx4 v[52:55], v[52:53], off
	v_add_u32_e32 v124, v58, v123
	s_waitcnt vmcnt(0)
	ds_write_b128 v124, v[0:3]
	ds_write_b128 v124, v[4:7] offset:17408
	v_lshrrev_b32_e32 v0, 3, v56
	s_movk_i32 s1, 0x90
	v_mul_lo_u32 v125, v0, s1
	v_lshrrev_b32_e32 v0, 4, v57
	v_mul_lo_u32 v127, v0, s0
	v_lshrrev_b32_e32 v0, 3, v57
	v_mul_lo_u32 v129, v0, s1
	v_add_u32_e32 v0, 0x200, v56
	v_lshrrev_b32_e32 v1, 4, v0
	v_lshrrev_b32_e32 v0, 3, v0
	v_mul_lo_u32 v133, v0, s1
	v_add_u32_e32 v0, 0x300, v56
	v_mul_lo_u32 v131, v1, s0
	v_lshrrev_b32_e32 v1, 4, v0
	v_mul_lo_u32 v135, v1, s0
	v_lshrrev_b32_e32 v0, 3, v0
	s_add_u32 s0, s16, 0x16000
	v_and_b32_e32 v144, 0x70, v112
	v_mul_lo_u32 v137, v0, s1
	v_add_u32_e32 v0, 0, v125
	s_addc_u32 s1, s17, 0
	v_add_u32_e32 v59, 0, v144
	v_add_u32_e32 v139, v0, v144
	v_add_u32_e32 v0, 0, v129
	s_add_u32 s28, s16, 0x1a000
	v_add_u32_e32 v126, v59, v125
	v_add_u32_e32 v128, v58, v127
	v_add_u32_e32 v130, v59, v129
	v_add_u32_e32 v132, v58, v131
	v_add_u32_e32 v134, v59, v133
	v_add_u32_e32 v136, v58, v135
	v_add_u32_e32 v138, v59, v137
	v_add_u32_e32 v140, v0, v144
	s_addc_u32 s29, s17, 0
	ds_write_b128 v126, v[8:11] offset:34816
	ds_write_b128 v128, v[12:15]
	ds_write_b128 v128, v[16:19] offset:17408
	ds_write_b128 v130, v[20:23] offset:34816
	ds_write_b128 v132, v[24:27]
	ds_write_b128 v132, v[28:31] offset:17408
	ds_write_b128 v134, v[32:35] offset:34816
	ds_write_b128 v136, v[36:39]
	ds_write_b128 v136, v[40:43] offset:17408
	ds_write_b128 v138, v[44:47] offset:34816
	ds_write_b128 v139, v[48:51] offset:53248
	ds_write_b128 v140, v[52:55] offset:53248
	s_add_u32 s34, s16, 0x1e000
	v_lshl_add_u64 v[0:1], s[0:1], 0, v[112:113]
	s_addc_u32 s35, s17, 0
	global_load_dwordx4 v[0:3], v[0:1], off
	v_lshl_add_u64 v[4:5], s[28:29], 0, v[112:113]
	global_load_dwordx4 v[4:7], v[4:5], off
	v_lshl_add_u64 v[8:9], s[34:35], 0, v[112:113]
	global_load_dwordx4 v[8:11], v[8:9], off
	v_lshl_add_u64 v[12:13], s[0:1], 0, v[114:115]
	global_load_dwordx4 v[12:15], v[12:13], off
	v_lshl_add_u64 v[16:17], s[28:29], 0, v[114:115]
	global_load_dwordx4 v[16:19], v[16:17], off
	v_lshl_add_u64 v[20:21], s[34:35], 0, v[114:115]
	global_load_dwordx4 v[20:23], v[20:21], off
	v_lshl_add_u64 v[24:25], s[0:1], 0, v[116:117]
	global_load_dwordx4 v[24:27], v[24:25], off
	v_lshl_add_u64 v[28:29], s[28:29], 0, v[116:117]
	global_load_dwordx4 v[28:31], v[28:29], off
	v_lshl_add_u64 v[32:33], s[34:35], 0, v[116:117]
	v_lshl_add_u64 v[36:37], s[0:1], 0, v[118:119]
	s_add_u32 s0, s16, 0x22000
	global_load_dwordx4 v[32:35], v[32:33], off
	s_addc_u32 s1, s17, 0
	global_load_dwordx4 v[36:39], v[36:37], off
	v_lshl_add_u64 v[40:41], s[28:29], 0, v[118:119]
	v_lshl_add_u64 v[48:49], s[0:1], 0, v[112:113]
	v_lshl_add_u64 v[52:53], s[0:1], 0, v[120:121]
	s_add_u32 s0, s16, 0x28000
	global_load_dwordx4 v[40:43], v[40:41], off
	v_lshl_add_u64 v[44:45], s[34:35], 0, v[118:119]
	s_addc_u32 s1, s17, 0
	global_load_dwordx4 v[44:47], v[44:45], off
	s_add_u32 s28, s16, 0x2c000
	global_load_dwordx4 v[48:51], v[48:49], off
	s_addc_u32 s29, s17, 0
	global_load_dwordx4 v[56:59], v[52:53], off
	s_add_u32 s34, s16, 0x30000
	v_lshl_add_u64 v[52:53], s[0:1], 0, v[112:113]
	s_addc_u32 s35, s17, 0
	global_load_dwordx4 v[52:55], v[52:53], off
	v_lshl_add_u64 v[60:61], s[28:29], 0, v[112:113]
	global_load_dwordx4 v[60:63], v[60:61], off
	v_lshl_add_u64 v[64:65], s[34:35], 0, v[112:113]
	global_load_dwordx4 v[64:67], v[64:65], off
	v_lshl_add_u64 v[68:69], s[0:1], 0, v[114:115]
	global_load_dwordx4 v[68:71], v[68:69], off
	v_lshl_add_u64 v[72:73], s[28:29], 0, v[114:115]
	global_load_dwordx4 v[72:75], v[72:73], off
	v_lshl_add_u64 v[76:77], s[34:35], 0, v[114:115]
	global_load_dwordx4 v[76:79], v[76:77], off
	v_lshl_add_u64 v[80:81], s[0:1], 0, v[116:117]
	global_load_dwordx4 v[80:83], v[80:81], off
	v_lshl_add_u64 v[84:85], s[28:29], 0, v[116:117]
	global_load_dwordx4 v[84:87], v[84:85], off
	v_lshl_add_u64 v[88:89], s[34:35], 0, v[116:117]
	global_load_dwordx4 v[88:91], v[88:89], off
	v_lshl_add_u64 v[92:93], s[0:1], 0, v[118:119]
	global_load_dwordx4 v[92:95], v[92:93], off
	v_lshl_add_u64 v[96:97], s[28:29], 0, v[118:119]
	s_add_u32 s0, s16, 0x34000
	global_load_dwordx4 v[96:99], v[96:97], off
	v_lshl_add_u64 v[100:101], s[34:35], 0, v[118:119]
	s_addc_u32 s1, s17, 0
	global_load_dwordx4 v[100:103], v[100:101], off
	v_lshl_add_u64 v[104:105], s[0:1], 0, v[112:113]
	global_load_dwordx4 v[104:107], v[104:105], off
	v_lshl_add_u64 v[108:109], s[0:1], 0, v[120:121]
	s_add_i32 s0, 0, 0x13800
	global_load_dwordx4 v[108:111], v[108:109], off
	v_add_u32_e32 v141, s0, v141
	s_add_i32 s0, 0, 0x17c00
	s_waitcnt lgkmcnt(0)
	s_barrier
	v_add_u32_e32 v142, s0, v144
	s_add_i32 s0, 0, 0x1c400
	v_add_u32_e32 v143, s0, v125
	v_add_u32_e32 v145, s0, v129
	v_add_u32_e32 v143, v143, v144
	v_add_u32_e32 v144, v145, v144
	s_branch .LBB0_511

.LBB0_511:
	s_min_u32 s0, s27, 60
	s_waitcnt vmcnt(14)
	s_cmp_eq_u32 s100, 0
	s_cbranch_scc1 .Lpf_nopub_a1
	s_mov_b64 exec, 1
	v_mov_b32_e32 v239, s27
	global_store_dword v238, v239, s[98:99]
	s_mov_b64 exec, -1
.Lpf_nopub_a1:
	ds_write_b128 v124, v[0:3] offset:62464
	v_add_u32_e32 v0, v141, v123
	s_add_i32 s0, s0, 3
	ds_write_b128 v0, v[4:7]
	v_add_u32_e32 v0, v142, v125
	s_mul_i32 s0, s3, s0
	ds_write_b128 v0, v[8:11]
	ds_write_b128 v128, v[12:15] offset:62464
	v_add_u32_e32 v0, v141, v127
	s_add_u32 s7, s16, s0
	ds_write_b128 v0, v[16:19]
	v_add_u32_e32 v0, v142, v129
	s_addc_u32 s38, s17, 0
	ds_write_b128 v0, v[20:23]
	ds_write_b128 v132, v[24:27] offset:62464
	v_add_u32_e32 v0, v141, v131
	s_add_u32 s0, s7, s6
	ds_write_b128 v0, v[28:31]
	v_add_u32_e32 v0, v142, v133
	s_addc_u32 s1, s38, 0
	ds_write_b128 v0, v[32:35]
	ds_write_b128 v136, v[36:39] offset:62464
	v_add_u32_e32 v0, v141, v135
	s_add_u32 s28, s7, s14
	ds_write_b128 v0, v[40:43]
	v_add_u32_e32 v0, v142, v137
	s_addc_u32 s29, s38, 0
	ds_write_b128 v0, v[44:47]
	ds_write_b128 v143, v[48:51]
	ds_write_b128 v144, v[56:59]
	s_add_u32 s34, s7, s15
	v_lshl_add_u64 v[0:1], s[0:1], 0, v[112:113]
	s_addc_u32 s35, s38, 0
	global_load_dwordx4 v[0:3], v[0:1], off
	v_lshl_add_u64 v[4:5], s[28:29], 0, v[112:113]
	global_load_dwordx4 v[4:7], v[4:5], off
	v_lshl_add_u64 v[8:9], s[34:35], 0, v[112:113]
	global_load_dwordx4 v[8:11], v[8:9], off
	v_lshl_add_u64 v[12:13], s[0:1], 0, v[114:115]
	global_load_dwordx4 v[12:15], v[12:13], off
	v_lshl_add_u64 v[16:17], s[28:29], 0, v[114:115]
	global_load_dwordx4 v[16:19], v[16:17], off
	v_lshl_add_u64 v[20:21], s[34:35], 0, v[114:115]
	global_load_dwordx4 v[20:23], v[20:21], off
	v_lshl_add_u64 v[24:25], s[0:1], 0, v[116:117]
	global_load_dwordx4 v[24:27], v[24:25], off
	v_lshl_add_u64 v[28:29], s[28:29], 0, v[116:117]
	global_load_dwordx4 v[28:31], v[28:29], off
	v_lshl_add_u64 v[32:33], s[34:35], 0, v[116:117]
	global_load_dwordx4 v[32:35], v[32:33], off
	v_lshl_add_u64 v[36:37], s[0:1], 0, v[118:119]
	global_load_dwordx4 v[36:39], v[36:37], off
	v_lshl_add_u64 v[40:41], s[28:29], 0, v[118:119]
	s_add_u32 s0, s7, s26
	global_load_dwordx4 v[40:43], v[40:41], off
	v_lshl_add_u64 v[44:45], s[34:35], 0, v[118:119]
	s_addc_u32 s1, s38, 0
	global_load_dwordx4 v[44:47], v[44:45], off
	v_lshl_add_u64 v[48:49], s[0:1], 0, v[112:113]
	global_load_dwordx4 v[48:51], v[48:49], off
	v_lshl_add_u64 v[56:57], s[0:1], 0, v[120:121]
	global_load_dwordx4 v[56:59], v[56:57], off
	s_waitcnt lgkmcnt(0)
	s_barrier
	s_waitcnt vmcnt(14)
	s_cmp_eq_u32 s100, 0
	s_cbranch_scc1 .Lpf_nopub_a0
	s_mov_b64 exec, 1
	v_mov_b32_e32 v239, s27
	v_or_b32_e32 v239, 1, v239
	global_store_dword v238, v239, s[98:99]
	s_mov_b64 exec, -1
.Lpf_nopub_a0:
	s_cmp_gt_u32 s27, 61
	s_cselect_b64 s[0:1], -1, 0
	s_and_b64 vcc, exec, s[0:1]
	s_cbranch_vccnz .LBB0_510
	ds_write_b128 v124, v[52:55]
	ds_write_b128 v124, v[60:63] offset:17408
	ds_write_b128 v126, v[64:67] offset:34816
	ds_write_b128 v128, v[68:71]
	ds_write_b128 v128, v[72:75] offset:17408
	ds_write_b128 v130, v[76:79] offset:34816
	ds_write_b128 v132, v[80:83]
	ds_write_b128 v132, v[84:87] offset:17408
	ds_write_b128 v134, v[88:91] offset:34816
	ds_write_b128 v136, v[92:95]
	ds_write_b128 v136, v[96:99] offset:17408
	ds_write_b128 v138, v[100:103] offset:34816
	ds_write_b128 v139, v[104:107] offset:53248
	ds_write_b128 v140, v[108:111] offset:53248
	s_branch .LBB0_510

.LBB0_517:
	v_add_u32_e32 v112, v108, v90
	s_min_u32 s0, s6, 60
	s_waitcnt vmcnt(10)
	s_cmp_eq_u32 s100, 0
	s_cbranch_scc1 .Lpf_nopub_b1
	s_mov_b64 exec, 1
	v_mov_b32_e32 v239, s6
	global_store_dword v238, v239, s[98:99]
	s_mov_b64 exec, -1
.Lpf_nopub_b1:
	ds_write_b128 v112, v[0:3]
	v_add_u32_e32 v0, v109, v92
	s_add_i32 s0, s0, 3
	ds_write_b128 v0, v[4:7]
	v_add_u32_e32 v0, v108, v94
	s_mul_i32 s0, s3, s0
	ds_write_b128 v0, v[8:11]
	v_add_u32_e32 v0, v109, v96
	s_add_u32 s7, s16, s0
	ds_write_b128 v0, v[12:15]
	v_add_u32_e32 v0, v108, v98
	s_addc_u32 s12, s17, 0
	ds_write_b128 v0, v[16:19]
	v_add_u32_e32 v0, v109, v100
	s_add_u32 s0, s7, s14
	ds_write_b128 v0, v[20:23]
	v_add_u32_e32 v0, v108, v102
	s_addc_u32 s1, s12, 0
	ds_write_b128 v0, v[24:27]
	v_add_u32_e32 v0, v109, v104
	s_add_u32 s8, s7, s15
	ds_write_b128 v0, v[28:31]
	ds_write_b128 v110, v[32:35]
	ds_write_b128 v111, v[40:43]
	s_addc_u32 s9, s12, 0
	v_lshl_add_u64 v[0:1], s[0:1], 0, v[80:81]
	global_load_dwordx4 v[0:3], v[0:1], off
	v_lshl_add_u64 v[4:5], s[8:9], 0, v[80:81]
	global_load_dwordx4 v[4:7], v[4:5], off
	v_lshl_add_u64 v[8:9], s[0:1], 0, v[82:83]
	global_load_dwordx4 v[8:11], v[8:9], off
	v_lshl_add_u64 v[12:13], s[8:9], 0, v[82:83]
	global_load_dwordx4 v[12:15], v[12:13], off
	v_lshl_add_u64 v[16:17], s[0:1], 0, v[84:85]
	global_load_dwordx4 v[16:19], v[16:17], off
	v_lshl_add_u64 v[20:21], s[8:9], 0, v[84:85]
	global_load_dwordx4 v[20:23], v[20:21], off
	v_lshl_add_u64 v[24:25], s[0:1], 0, v[86:87]
	s_add_u32 s0, s7, s26
	global_load_dwordx4 v[24:27], v[24:25], off
	v_lshl_add_u64 v[28:29], s[8:9], 0, v[86:87]
	s_addc_u32 s1, s12, 0
	global_load_dwordx4 v[28:31], v[28:29], off
	v_lshl_add_u64 v[32:33], s[0:1], 0, v[80:81]
	global_load_dwordx4 v[32:35], v[32:33], off
	v_lshl_add_u64 v[40:41], s[0:1], 0, v[88:89]
	global_load_dwordx4 v[40:43], v[40:41], off
	s_waitcnt lgkmcnt(0)
	s_barrier
	s_waitcnt vmcnt(10)
	s_cmp_eq_u32 s100, 0
	s_cbranch_scc1 .Lpf_nopub_b0
	s_mov_b64 exec, 1
	v_mov_b32_e32 v239, s6
	v_or_b32_e32 v239, 1, v239
	global_store_dword v238, v239, s[98:99]
	s_mov_b64 exec, -1
.Lpf_nopub_b0:
	s_cmp_gt_u32 s6, 61
	s_cselect_b64 s[0:1], -1, 0
	s_and_b64 vcc, exec, s[0:1]
	s_cbranch_vccnz .LBB0_516
	ds_write_b128 v91, v[36:39] offset:17408
	ds_write_b128 v93, v[44:47] offset:34816
	ds_write_b128 v95, v[48:51] offset:17408
	ds_write_b128 v97, v[52:55] offset:34816
	ds_write_b128 v99, v[56:59] offset:17408
	ds_write_b128 v101, v[60:63] offset:34816
	ds_write_b128 v103, v[64:67] offset:17408
	ds_write_b128 v105, v[68:71] offset:34816
	ds_write_b128 v106, v[72:75] offset:53248
	ds_write_b128 v107, v[76:79] offset:53248
	s_branch .LBB0_516

	.amdhsa_kernel _Z14fwd_megakernel4Args
		.amdhsa_group_segment_fixed_size 0
		.amdhsa_private_segment_fixed_size 0
		.amdhsa_kernarg_size 408
		.amdhsa_user_sgpr_count 2
		.amdhsa_user_sgpr_dispatch_ptr 0
		.amdhsa_user_sgpr_queue_ptr 0
		.amdhsa_user_sgpr_kernarg_segment_ptr 1
		.amdhsa_user_sgpr_dispatch_id 0
		.amdhsa_user_sgpr_kernarg_preload_length 0
		.amdhsa_user_sgpr_kernarg_preload_offset 0
		.amdhsa_user_sgpr_private_segment_size 0
		.amdhsa_uses_dynamic_stack 0
		.amdhsa_enable_private_segment 0
		.amdhsa_system_sgpr_workgroup_id_x 1
		.amdhsa_system_sgpr_workgroup_id_y 0
		.amdhsa_system_sgpr_workgroup_id_z 0
		.amdhsa_system_sgpr_workgroup_info 0
		.amdhsa_system_vgpr_workitem_id 2
		.amdhsa_next_free_vgpr 241
		.amdhsa_next_free_sgpr 101
		.amdhsa_accum_offset 244
		.amdhsa_reserve_vcc 1
		.amdhsa_float_round_mode_32 0
		.amdhsa_float_round_mode_16_64 0
		.amdhsa_float_denorm_mode_32 3
		.amdhsa_float_denorm_mode_16_64 3
		.amdhsa_dx10_clamp 1
		.amdhsa_ieee_mode 1
		.amdhsa_fp16_overflow 0
		.amdhsa_tg_split 0
		.amdhsa_exception_fp_ieee_invalid_op 0
		.amdhsa_exception_fp_denorm_src 0
		.amdhsa_exception_fp_ieee_div_zero 0
		.amdhsa_exception_fp_ieee_overflow 0
		.amdhsa_exception_fp_ieee_underflow 0
		.amdhsa_exception_fp_ieee_inexact 0
		.amdhsa_exception_int_div_zero 0
	.end_amdhsa_kernel

amdhsa.kernels:
  - .agpr_count:     0
    .args:
      - .offset:         0
        .size:           152
        .value_kind:     by_value
      - .offset:         152
        .size:           4
        .value_kind:     hidden_block_count_x
      - .offset:         156
        .size:           4
        .value_kind:     hidden_block_count_y
      - .offset:         160
        .size:           4
        .value_kind:     hidden_block_count_z
      - .offset:         164
        .size:           2
        .value_kind:     hidden_group_size_x
      - .offset:         166
        .size:           2
        .value_kind:     hidden_group_size_y
      - .offset:         168
        .size:           2
        .value_kind:     hidden_group_size_z
      - .offset:         170
        .size:           2
        .value_kind:     hidden_remainder_x
      - .offset:         172
        .size:           2
        .value_kind:     hidden_remainder_y
      - .offset:         174
        .size:           2
        .value_kind:     hidden_remainder_z
      - .offset:         192
        .size:           8
        .value_kind:     hidden_global_offset_x
      - .offset:         200
        .size:           8
        .value_kind:     hidden_global_offset_y
      - .offset:         208
        .size:           8
        .value_kind:     hidden_global_offset_z
      - .offset:         216
        .size:           2
        .value_kind:     hidden_grid_dims
      - .offset:         240
        .size:           8
        .value_kind:     hidden_multigrid_sync_arg
      - .offset:         272
        .size:           4
        .value_kind:     hidden_dynamic_lds_size
    .group_segment_fixed_size: 0
    .kernarg_segment_align: 8
    .kernarg_segment_size: 408
    .language:       OpenCL C
    .language_version:
      - 2
      - 0
    .max_flat_workgroup_size: 512
    .name:           _Z14fwd_megakernel4Args
    .private_segment_fixed_size: 0
    .sgpr_count:     107
    .sgpr_spill_count: 4
    .symbol:         _Z14fwd_megakernel4Args.kd
    .uniform_work_group_size: 1
    .uses_dynamic_stack: false
    .vgpr_count:     241
    .vgpr_spill_count: 0
    .wavefront_size: 64
